# baseline (speedup 1.0000x reference)
; __global__ void __launch_bounds__(NTHR, 2) hymba_fwd(Args args) {
;     ...
;     for (int ph = lo; ph < hi; ++ph) {
;         int l = ph / NPH; const int k = ph % NPH;
;         if (k == 3 || k == 11) continue;
;         asm volatile("" : "+s"(l));
;         int G = gridDim.x, bid = blockIdx.x; asm volatile("" : "+s"(G), "+s"(bid));
;         typedef __attribute__((address_space(4))) const unsigned char* kptr_t;
;         kptr_t kp = (kptr_t)__builtin_amdgcn_kernarg_segment_ptr(); asm volatile("" : "+s"(kp));
;         int tid = threadIdx.x; asm volatile("" : "+v"(tid));
;         const int lane = tid & 63, wave = __builtin_amdgcn_readfirstlane(tid >> 6);
;         const int gw = bid * NWAVES + wave, NGW = G * NWAVES;
;         unsigned char* ws = *(unsigned char* const __attribute__((address_space(4)))*)(kp + 376);
;         float* xout = *(float* const __attribute__((address_space(4)))*)(kp + 368);
.LBB0_20:
	s_lshr_b32 s5, s54, 1
	s_mul_hi_i32 s0, s5, 0x92492493
	s_add_i32 s0, s0, s5
	s_lshr_b32 s1, s0, 31
	s_ashr_i32 s0, s0, 3
	s_add_i32 s4, s0, s1
	s_mul_i32 s0, s4, 14
	s_sub_i32 s5, s5, s0
	s_cmp_eq_u32 s5, 1
	s_cselect_b32 s0, 1, 0
	s_cmp_eq_u32 s5, 4
	s_cselect_b32 s1, 1, 0
	s_or_b32 s0, s0, s1
	s_cmp_eq_u32 s5, 7
	s_cselect_b32 s1, 1, 0
	s_or_b32 s0, s0, s1
	s_cmp_eq_u32 s5, 12
	s_cselect_b32 s1, 1, 0
	s_cmp_eq_u32 s4, 0
	s_cselect_b32 s1, s1, 0
	s_or_b32 s0, s0, s1
	s_bitcmp1_b32 s54, 0
	s_cbranch_scc1 .Lhdr_rep1
	v_writelane_b32 v255, s0, 62
	s_mov_b32 s0, 0
	s_mov_b32 s1, 0xa07f
	v_writelane_b32 v255, s0, 61
	v_writelane_b32 v255, s1, 59
	s_movk_i32 s0, 0x2c00
	s_cmp_eq_u32 s4, 0
	s_cselect_b32 s0, s0, 0
	s_mov_b32 s1, 0x9fff
	v_writelane_b32 v255, s0, 57
	v_writelane_b32 v255, s1, 56
	s_branch .Lhdr_common
.Lhdr_rep1:
	s_cmp_eq_u32 s0, 0
	s_mov_b64 s[0:1], -1
	s_cbranch_scc1 .LBB0_24
	s_mov_b32 s0, 0x5600
	s_mov_b32 s1, 0x7fff
	s_cmp_eq_u32 s5, 1
	s_cmov_b32 s0, 0x2c00
	s_cmov_b32 s1, 0x55ff
	s_cmp_eq_u32 s5, 12
	s_cmov_b32 s0, 0
	s_cmov_b32 s1, 0x2bff
	s_cmp_eq_u32 s5, 7
	s_cmov_b32 s0, 0x8000
	s_cmov_b32 s1, 0x9fff
	v_writelane_b32 v255, s0, 60
	v_writelane_b32 v255, s1, 59
	s_mov_b32 s0, 0x80
	s_cmov_b32 s0, 64
	s_mov_b32 s1, 1
	v_writelane_b32 v255, s0, 58
	v_writelane_b32 v255, s1, 61
	s_mov_b32 s0, 0
	s_mov_b32 s1, 0x7fffffff
	v_writelane_b32 v255, s0, 62
	v_writelane_b32 v255, s1, 57
	v_writelane_b32 v255, s0, 56
	s_cmp_eq_u32 s5, 12
	s_addc_u32 s4, s4, 0
	s_mov_b32 s5, 0

; __device__ __forceinline__ void rg_scan_seg(const int tid, const float* RGA, const float* RGB, float* RGC, float* RGH, float* SEG, int seg) {
;     const int c = tid;
;     float h = 0.f, A = 1.f;
;     for (int t = seg * RGSEGL; t < (seg + 1) * RGSEGL; t += 8) {
;         float a[8], b[8];
; #pragma unroll
;         for (int i = 0; i < 8; ++i) { a[i] = RGA[(size_t)(t + i) * GW + c]; b[i] = RGB[(size_t)(t + i) * GW + c]; }
; #pragma unroll
;         for (int i = 0; i < 8; ++i) { h = a[i] * h + b[i]; A *= a[i]; RGH[(size_t)(t + i) * GW + c] = h; RGC[(size_t)(t + i) * GW + c] = A; }
;     }
;     SEG[seg * GW + c] = A; SEG[(RGSEG + seg) * GW + c] = h;
; }
.LBB0_306:
	v_readlane_b32 s0, v254, 39
	s_cmpk_gt_i32 s0, 0x7f
	v_readlane_b32 s45, v254, 38
	s_waitcnt lgkmcnt(0)
	s_barrier
	s_cbranch_scc1 .LBB0_313
	v_readlane_b32 s44, v254, 39
	s_waitcnt vmcnt(0)
	v_cmp_gt_u32_e32 vcc, 0x80, v148
	s_and_saveexec_b64 s[4:5], vcc
	s_cbranch_execz .Lrgs_done
	v_lshlrev_b32_e32 v0, 4, v148
.Lrgs_seg:
	s_lshl_b32 s0, s44, 17
	s_add_u32 s6, s18, s0
	s_addc_u32 s7, s19, 0
	s_add_u32 s20, s6, 0x23a00000
	s_addc_u32 s21, s7, 0
	s_add_u32 s22, s6, 0x24a00000
	s_addc_u32 s23, s7, 0
	s_add_u32 s24, s6, 0x26300000
	s_addc_u32 s25, s7, 0
	s_add_u32 s26, s6, 0x27300000
	s_addc_u32 s27, s7, 0
	v_mov_b32_e32 v16, 0
	v_mov_b32_e32 v17, 0
	v_mov_b32_e32 v18, 0
	v_mov_b32_e32 v19, 0
	v_mov_b32_e32 v20, 1.0
	v_mov_b32_e32 v21, 1.0
	v_mov_b32_e32 v22, 1.0
	v_mov_b32_e32 v23, 1.0
	global_load_dwordx4 v[32:35], v0, s[20:21] offset:0
	global_load_dwordx4 v[36:39], v0, s[22:23] offset:0
	global_load_dwordx4 v[40:43], v0, s[20:21] offset:2048
	global_load_dwordx4 v[44:47], v0, s[22:23] offset:2048
	s_add_u32 s20, s20, 0x1000
	s_addc_u32 s21, s21, 0
	s_add_u32 s22, s22, 0x1000
	s_addc_u32 s23, s23, 0
	global_load_dwordx4 v[48:51], v0, s[20:21] offset:0
	global_load_dwordx4 v[52:55], v0, s[22:23] offset:0
	global_load_dwordx4 v[56:59], v0, s[20:21] offset:2048
	global_load_dwordx4 v[60:63], v0, s[22:23] offset:2048
	s_add_u32 s20, s20, 0x1000
	s_addc_u32 s21, s21, 0
	s_add_u32 s22, s22, 0x1000
	s_addc_u32 s23, s23, 0
	global_load_dwordx4 v[64:67], v0, s[20:21] offset:0
	global_load_dwordx4 v[68:71], v0, s[22:23] offset:0
	global_load_dwordx4 v[72:75], v0, s[20:21] offset:2048
	global_load_dwordx4 v[76:79], v0, s[22:23] offset:2048
	s_add_u32 s20, s20, 0x1000
	s_addc_u32 s21, s21, 0
	s_add_u32 s22, s22, 0x1000
	s_addc_u32 s23, s23, 0
	global_load_dwordx4 v[80:83], v0, s[20:21] offset:0
	global_load_dwordx4 v[84:87], v0, s[22:23] offset:0
	global_load_dwordx4 v[88:91], v0, s[20:21] offset:2048
	global_load_dwordx4 v[92:95], v0, s[22:23] offset:2048
	s_add_u32 s20, s20, 0x1000
	s_addc_u32 s21, s21, 0
	s_add_u32 s22, s22, 0x1000
	s_addc_u32 s23, s23, 0
	s_waitcnt vmcnt(14)
	v_fma_f32 v16, v32, v16, v36
	v_mul_f32_e32 v20, v20, v32
	v_fma_f32 v17, v33, v17, v37
	v_mul_f32_e32 v21, v21, v33
	v_fma_f32 v18, v34, v18, v38
	v_mul_f32_e32 v22, v22, v34
	v_fma_f32 v19, v35, v19, v39
	v_mul_f32_e32 v23, v23, v35
	global_store_dwordx4 v0, v[16:19], s[24:25] offset:0
	global_store_dwordx4 v0, v[20:23], s[26:27] offset:0
	global_load_dwordx4 v[32:35], v0, s[20:21] offset:0
	global_load_dwordx4 v[36:39], v0, s[22:23] offset:0
	s_waitcnt vmcnt(16)
	v_fma_f32 v16, v40, v16, v44
	v_mul_f32_e32 v20, v20, v40
	v_fma_f32 v17, v41, v17, v45
	v_mul_f32_e32 v21, v21, v41
	v_fma_f32 v18, v42, v18, v46
	v_mul_f32_e32 v22, v22, v42
	v_fma_f32 v19, v43, v19, v47
	v_mul_f32_e32 v23, v23, v43
	global_store_dwordx4 v0, v[16:19], s[24:25] offset:2048
	global_store_dwordx4 v0, v[20:23], s[26:27] offset:2048
	global_load_dwordx4 v[40:43], v0, s[20:21] offset:2048
	global_load_dwordx4 v[44:47], v0, s[22:23] offset:2048
	s_add_u32 s24, s24, 0x1000
	s_addc_u32 s25, s25, 0
	s_add_u32 s26, s26, 0x1000
	s_addc_u32 s27, s27, 0
	s_add_u32 s20, s20, 0x1000
	s_addc_u32 s21, s21, 0
	s_add_u32 s22, s22, 0x1000
	s_addc_u32 s23, s23, 0
	s_waitcnt vmcnt(18)
	v_fma_f32 v16, v48, v16, v52
	v_mul_f32_e32 v20, v20, v48
	v_fma_f32 v17, v49, v17, v53
	v_mul_f32_e32 v21, v21, v49
	v_fma_f32 v18, v50, v18, v54
	v_mul_f32_e32 v22, v22, v50
	v_fma_f32 v19, v51, v19, v55
	v_mul_f32_e32 v23, v23, v51
	global_store_dwordx4 v0, v[16:19], s[24:25] offset:0
	global_store_dwordx4 v0, v[20:23], s[26:27] offset:0
	global_load_dwordx4 v[48:51], v0, s[20:21] offset:0
	global_load_dwordx4 v[52:55], v0, s[22:23] offset:0
	s_waitcnt vmcnt(20)
	v_fma_f32 v16, v56, v16, v60
	v_mul_f32_e32 v20, v20, v56
	v_fma_f32 v17, v57, v17, v61
	v_mul_f32_e32 v21, v21, v57
	v_fma_f32 v18, v58, v18, v62
	v_mul_f32_e32 v22, v22, v58
	v_fma_f32 v19, v59, v19, v63
	v_mul_f32_e32 v23, v23, v59
	global_store_dwordx4 v0, v[16:19], s[24:25] offset:2048
	global_store_dwordx4 v0, v[20:23], s[26:27] offset:2048
	global_load_dwordx4 v[56:59], v0, s[20:21] offset:2048
	global_load_dwordx4 v[60:63], v0, s[22:23] offset:2048
	s_add_u32 s24, s24, 0x1000
	s_addc_u32 s25, s25, 0
	s_add_u32 s26, s26, 0x1000
	s_addc_u32 s27, s27, 0
	s_add_u32 s20, s20, 0x1000
	s_addc_u32 s21, s21, 0
	s_add_u32 s22, s22, 0x1000
	s_addc_u32 s23, s23, 0
	s_waitcnt vmcnt(22)
	v_fma_f32 v16, v64, v16, v68
	v_mul_f32_e32 v20, v20, v64
	v_fma_f32 v17, v65, v17, v69
	v_mul_f32_e32 v21, v21, v65
	v_fma_f32 v18, v66, v18, v70
	v_mul_f32_e32 v22, v22, v66
	v_fma_f32 v19, v67, v19, v71
	v_mul_f32_e32 v23, v23, v67
	global_store_dwordx4 v0, v[16:19], s[24:25] offset:0
	global_store_dwordx4 v0, v[20:23], s[26:27] offset:0
	global_load_dwordx4 v[64:67], v0, s[20:21] offset:0
	global_load_dwordx4 v[68:71], v0, s[22:23] offset:0
	s_waitcnt vmcnt(24)
	v_fma_f32 v16, v72, v16, v76
	v_mul_f32_e32 v20, v20, v72
	v_fma_f32 v17, v73, v17, v77
	v_mul_f32_e32 v21, v21, v73
	v_fma_f32 v18, v74, v18, v78
	v_mul_f32_e32 v22, v22, v74
	v_fma_f32 v19, v75, v19, v79
	v_mul_f32_e32 v23, v23, v75
	global_store_dwordx4 v0, v[16:19], s[24:25] offset:2048
	global_store_dwordx4 v0, v[20:23], s[26:27] offset:2048
	global_load_dwordx4 v[72:75], v0, s[20:21] offset:2048
	global_load_dwordx4 v[76:79], v0, s[22:23] offset:2048
	s_add_u32 s24, s24, 0x1000
	s_addc_u32 s25, s25, 0
	s_add_u32 s26, s26, 0x1000
	s_addc_u32 s27, s27, 0
	s_add_u32 s20, s20, 0x1000
	s_addc_u32 s21, s21, 0
	s_add_u32 s22, s22, 0x1000
	s_addc_u32 s23, s23, 0
	s_waitcnt vmcnt(26)
	v_fma_f32 v16, v80, v16, v84
	v_mul_f32_e32 v20, v20, v80
	v_fma_f32 v17, v81, v17, v85
	v_mul_f32_e32 v21, v21, v81
	v_fma_f32 v18, v82, v18, v86
	v_mul_f32_e32 v22, v22, v82
	v_fma_f32 v19, v83, v19, v87
	v_mul_f32_e32 v23, v23, v83
	global_store_dwordx4 v0, v[16:19], s[24:25] offset:0
	global_store_dwordx4 v0, v[20:23], s[26:27] offset:0
	global_load_dwordx4 v[80:83], v0, s[20:21] offset:0
	global_load_dwordx4 v[84:87], v0, s[22:23] offset:0
	s_waitcnt vmcnt(28)
	v_fma_f32 v16, v88, v16, v92
	v_mul_f32_e32 v20, v20, v88
	v_fma_f32 v17, v89, v17, v93
	v_mul_f32_e32 v21, v21, v89
	v_fma_f32 v18, v90, v18, v94
	v_mul_f32_e32 v22, v22, v90
	v_fma_f32 v19, v91, v19, v95
	v_mul_f32_e32 v23, v23, v91
	global_store_dwordx4 v0, v[16:19], s[24:25] offset:2048
	global_store_dwordx4 v0, v[20:23], s[26:27] offset:2048
	global_load_dwordx4 v[88:91], v0, s[20:21] offset:2048
	global_load_dwordx4 v[92:95], v0, s[22:23] offset:2048
	s_add_u32 s24, s24, 0x1000
	s_addc_u32 s25, s25, 0
	s_add_u32 s26, s26, 0x1000
	s_addc_u32 s27, s27, 0
	s_add_u32 s20, s20, 0x1000
	s_addc_u32 s21, s21, 0
	s_add_u32 s22, s22, 0x1000
	s_addc_u32 s23, s23, 0
	s_mov_b32 s1, 6
; __device__ __forceinline__ void rg_scan_seg(const int tid, const float* RGA, const float* RGB, float* RGC, float* RGH, float* SEG, int seg) {
;     ...
;     for (int t = seg * RGSEGL; t < (seg + 1) * RGSEGL; t += 8) {
;         float a[8], b[8];
; #pragma unroll
;         for (int i = 0; i < 8; ++i) { a[i] = RGA[(size_t)(t + i) * GW + c]; b[i] = RGB[(size_t)(t + i) * GW + c]; }
; #pragma unroll
;         for (int i = 0; i < 8; ++i) { h = a[i] * h + b[i]; A *= a[i]; RGH[(size_t)(t + i) * GW + c] = h; RGC[(size_t)(t + i) * GW + c] = A; }
.Lrgs_mid:
	s_waitcnt vmcnt(28)
	v_fma_f32 v16, v32, v16, v36
	v_mul_f32_e32 v20, v20, v32
	v_fma_f32 v17, v33, v17, v37
	v_mul_f32_e32 v21, v21, v33
	v_fma_f32 v18, v34, v18, v38
	v_mul_f32_e32 v22, v22, v34
	v_fma_f32 v19, v35, v19, v39
	v_mul_f32_e32 v23, v23, v35
	global_store_dwordx4 v0, v[16:19], s[24:25] offset:0
	global_store_dwordx4 v0, v[20:23], s[26:27] offset:0
	global_load_dwordx4 v[32:35], v0, s[20:21] offset:0
	global_load_dwordx4 v[36:39], v0, s[22:23] offset:0
	s_waitcnt vmcnt(28)
	v_fma_f32 v16, v40, v16, v44
	v_mul_f32_e32 v20, v20, v40
	v_fma_f32 v17, v41, v17, v45
	v_mul_f32_e32 v21, v21, v41
	v_fma_f32 v18, v42, v18, v46
	v_mul_f32_e32 v22, v22, v42
	v_fma_f32 v19, v43, v19, v47
	v_mul_f32_e32 v23, v23, v43
	global_store_dwordx4 v0, v[16:19], s[24:25] offset:2048
	global_store_dwordx4 v0, v[20:23], s[26:27] offset:2048
	global_load_dwordx4 v[40:43], v0, s[20:21] offset:2048
	global_load_dwordx4 v[44:47], v0, s[22:23] offset:2048
	s_add_u32 s24, s24, 0x1000
	s_addc_u32 s25, s25, 0
	s_add_u32 s26, s26, 0x1000
	s_addc_u32 s27, s27, 0
	s_add_u32 s20, s20, 0x1000
	s_addc_u32 s21, s21, 0
	s_add_u32 s22, s22, 0x1000
	s_addc_u32 s23, s23, 0
	s_waitcnt vmcnt(28)
	v_fma_f32 v16, v48, v16, v52
	v_mul_f32_e32 v20, v20, v48
	v_fma_f32 v17, v49, v17, v53
	v_mul_f32_e32 v21, v21, v49
	v_fma_f32 v18, v50, v18, v54
	v_mul_f32_e32 v22, v22, v50
	v_fma_f32 v19, v51, v19, v55
	v_mul_f32_e32 v23, v23, v51
	global_store_dwordx4 v0, v[16:19], s[24:25] offset:0
	global_store_dwordx4 v0, v[20:23], s[26:27] offset:0
	global_load_dwordx4 v[48:51], v0, s[20:21] offset:0
	global_load_dwordx4 v[52:55], v0, s[22:23] offset:0
	s_waitcnt vmcnt(28)
	v_fma_f32 v16, v56, v16, v60
	v_mul_f32_e32 v20, v20, v56
	v_fma_f32 v17, v57, v17, v61
	v_mul_f32_e32 v21, v21, v57
	v_fma_f32 v18, v58, v18, v62
	v_mul_f32_e32 v22, v22, v58
	v_fma_f32 v19, v59, v19, v63
	v_mul_f32_e32 v23, v23, v59
	global_store_dwordx4 v0, v[16:19], s[24:25] offset:2048
	global_store_dwordx4 v0, v[20:23], s[26:27] offset:2048
	global_load_dwordx4 v[56:59], v0, s[20:21] offset:2048
	global_load_dwordx4 v[60:63], v0, s[22:23] offset:2048
	s_add_u32 s24, s24, 0x1000
	s_addc_u32 s25, s25, 0
	s_add_u32 s26, s26, 0x1000
	s_addc_u32 s27, s27, 0
	s_add_u32 s20, s20, 0x1000
	s_addc_u32 s21, s21, 0
	s_add_u32 s22, s22, 0x1000
	s_addc_u32 s23, s23, 0
	s_waitcnt vmcnt(28)
	v_fma_f32 v16, v64, v16, v68
	v_mul_f32_e32 v20, v20, v64
	v_fma_f32 v17, v65, v17, v69
	v_mul_f32_e32 v21, v21, v65
	v_fma_f32 v18, v66, v18, v70
	v_mul_f32_e32 v22, v22, v66
	v_fma_f32 v19, v67, v19, v71
	v_mul_f32_e32 v23, v23, v67
	global_store_dwordx4 v0, v[16:19], s[24:25] offset:0
	global_store_dwordx4 v0, v[20:23], s[26:27] offset:0
	global_load_dwordx4 v[64:67], v0, s[20:21] offset:0
	global_load_dwordx4 v[68:71], v0, s[22:23] offset:0
	s_waitcnt vmcnt(28)
	v_fma_f32 v16, v72, v16, v76
	v_mul_f32_e32 v20, v20, v72
	v_fma_f32 v17, v73, v17, v77
	v_mul_f32_e32 v21, v21, v73
	v_fma_f32 v18, v74, v18, v78
	v_mul_f32_e32 v22, v22, v74
	v_fma_f32 v19, v75, v19, v79
	v_mul_f32_e32 v23, v23, v75
	global_store_dwordx4 v0, v[16:19], s[24:25] offset:2048
	global_store_dwordx4 v0, v[20:23], s[26:27] offset:2048
	global_load_dwordx4 v[72:75], v0, s[20:21] offset:2048
	global_load_dwordx4 v[76:79], v0, s[22:23] offset:2048
	s_add_u32 s24, s24, 0x1000
	s_addc_u32 s25, s25, 0
	s_add_u32 s26, s26, 0x1000
	s_addc_u32 s27, s27, 0
	s_add_u32 s20, s20, 0x1000
	s_addc_u32 s21, s21, 0
	s_add_u32 s22, s22, 0x1000
	s_addc_u32 s23, s23, 0
	s_waitcnt vmcnt(28)
	v_fma_f32 v16, v80, v16, v84
	v_mul_f32_e32 v20, v20, v80
	v_fma_f32 v17, v81, v17, v85
	v_mul_f32_e32 v21, v21, v81
	v_fma_f32 v18, v82, v18, v86
	v_mul_f32_e32 v22, v22, v82
	v_fma_f32 v19, v83, v19, v87
	v_mul_f32_e32 v23, v23, v83
	global_store_dwordx4 v0, v[16:19], s[24:25] offset:0
	global_store_dwordx4 v0, v[20:23], s[26:27] offset:0
	global_load_dwordx4 v[80:83], v0, s[20:21] offset:0
	global_load_dwordx4 v[84:87], v0, s[22:23] offset:0
	s_waitcnt vmcnt(28)
	v_fma_f32 v16, v88, v16, v92
	v_mul_f32_e32 v20, v20, v88
	v_fma_f32 v17, v89, v17, v93
	v_mul_f32_e32 v21, v21, v89
	v_fma_f32 v18, v90, v18, v94
	v_mul_f32_e32 v22, v22, v90
	v_fma_f32 v19, v91, v19, v95
	v_mul_f32_e32 v23, v23, v91
	global_store_dwordx4 v0, v[16:19], s[24:25] offset:2048
	global_store_dwordx4 v0, v[20:23], s[26:27] offset:2048
	global_load_dwordx4 v[88:91], v0, s[20:21] offset:2048
	global_load_dwordx4 v[92:95], v0, s[22:23] offset:2048
	s_add_u32 s24, s24, 0x1000
	s_addc_u32 s25, s25, 0
	s_add_u32 s26, s26, 0x1000
	s_addc_u32 s27, s27, 0
	s_add_u32 s20, s20, 0x1000
	s_addc_u32 s21, s21, 0
	s_add_u32 s22, s22, 0x1000
	s_addc_u32 s23, s23, 0
	s_sub_i32 s1, s1, 1
	s_cmp_lg_u32 s1, 0
	s_cbranch_scc1 .Lrgs_mid
; #define SREP(bit) for (int rep_ = 0; rep_ < (((SUBDUP >> (bit)) & 1) ? 2 : 1); ++rep_)
; __device__ __forceinline__ void rg_scan_seg(const int tid, const float* RGA, const float* RGB, float* RGC, float* RGH, float* SEG, int seg) {
;     ...
;         for (int i = 0; i < 8; ++i) { h = a[i] * h + b[i]; A *= a[i]; RGH[(size_t)(t + i) * GW + c] = h; RGC[(size_t)(t + i) * GW + c] = A; }
;     }
;     SEG[seg * GW + c] = A; SEG[(RGSEG + seg) * GW + c] = h;
; }
; __global__ void __launch_bounds__(NTHR, 2) hymba_fwd(Args args) {
;     ...
;             SREP(6) for (int sgi = bid; sgi < RGSEG; sgi += G) rg_scan_seg(tid, WSP(float, WS_RGA), WSP(float, WS_RGB), WSP(float, WS_RGC), WSP(float, WS_RGH), WSP(float, WS_SEG), sgi);
	s_waitcnt vmcnt(28)
	v_fma_f32 v16, v32, v16, v36
	v_mul_f32_e32 v20, v20, v32
	v_fma_f32 v17, v33, v17, v37
	v_mul_f32_e32 v21, v21, v33
	v_fma_f32 v18, v34, v18, v38
	v_mul_f32_e32 v22, v22, v34
	v_fma_f32 v19, v35, v19, v39
	v_mul_f32_e32 v23, v23, v35
	global_store_dwordx4 v0, v[16:19], s[24:25] offset:0
	global_store_dwordx4 v0, v[20:23], s[26:27] offset:0
	s_waitcnt vmcnt(26)
	v_fma_f32 v16, v40, v16, v44
	v_mul_f32_e32 v20, v20, v40
	v_fma_f32 v17, v41, v17, v45
	v_mul_f32_e32 v21, v21, v41
	v_fma_f32 v18, v42, v18, v46
	v_mul_f32_e32 v22, v22, v42
	v_fma_f32 v19, v43, v19, v47
	v_mul_f32_e32 v23, v23, v43
	global_store_dwordx4 v0, v[16:19], s[24:25] offset:2048
	global_store_dwordx4 v0, v[20:23], s[26:27] offset:2048
	s_add_u32 s24, s24, 0x1000
	s_addc_u32 s25, s25, 0
	s_add_u32 s26, s26, 0x1000
	s_addc_u32 s27, s27, 0
	s_waitcnt vmcnt(24)
	v_fma_f32 v16, v48, v16, v52
	v_mul_f32_e32 v20, v20, v48
	v_fma_f32 v17, v49, v17, v53
	v_mul_f32_e32 v21, v21, v49
	v_fma_f32 v18, v50, v18, v54
	v_mul_f32_e32 v22, v22, v50
	v_fma_f32 v19, v51, v19, v55
	v_mul_f32_e32 v23, v23, v51
	global_store_dwordx4 v0, v[16:19], s[24:25] offset:0
	global_store_dwordx4 v0, v[20:23], s[26:27] offset:0
	s_waitcnt vmcnt(22)
	v_fma_f32 v16, v56, v16, v60
	v_mul_f32_e32 v20, v20, v56
	v_fma_f32 v17, v57, v17, v61
	v_mul_f32_e32 v21, v21, v57
	v_fma_f32 v18, v58, v18, v62
	v_mul_f32_e32 v22, v22, v58
	v_fma_f32 v19, v59, v19, v63
	v_mul_f32_e32 v23, v23, v59
	global_store_dwordx4 v0, v[16:19], s[24:25] offset:2048
	global_store_dwordx4 v0, v[20:23], s[26:27] offset:2048
	s_add_u32 s24, s24, 0x1000
	s_addc_u32 s25, s25, 0
	s_add_u32 s26, s26, 0x1000
	s_addc_u32 s27, s27, 0
	s_waitcnt vmcnt(20)
	v_fma_f32 v16, v64, v16, v68
	v_mul_f32_e32 v20, v20, v64
	v_fma_f32 v17, v65, v17, v69
	v_mul_f32_e32 v21, v21, v65
	v_fma_f32 v18, v66, v18, v70
	v_mul_f32_e32 v22, v22, v66
	v_fma_f32 v19, v67, v19, v71
	v_mul_f32_e32 v23, v23, v67
	global_store_dwordx4 v0, v[16:19], s[24:25] offset:0
	global_store_dwordx4 v0, v[20:23], s[26:27] offset:0
	s_waitcnt vmcnt(18)
	v_fma_f32 v16, v72, v16, v76
	v_mul_f32_e32 v20, v20, v72
	v_fma_f32 v17, v73, v17, v77
	v_mul_f32_e32 v21, v21, v73
	v_fma_f32 v18, v74, v18, v78
	v_mul_f32_e32 v22, v22, v74
	v_fma_f32 v19, v75, v19, v79
	v_mul_f32_e32 v23, v23, v75
	global_store_dwordx4 v0, v[16:19], s[24:25] offset:2048
	global_store_dwordx4 v0, v[20:23], s[26:27] offset:2048
	s_add_u32 s24, s24, 0x1000
	s_addc_u32 s25, s25, 0
	s_add_u32 s26, s26, 0x1000
	s_addc_u32 s27, s27, 0
	s_waitcnt vmcnt(16)
	v_fma_f32 v16, v80, v16, v84
	v_mul_f32_e32 v20, v20, v80
	v_fma_f32 v17, v81, v17, v85
	v_mul_f32_e32 v21, v21, v81
	v_fma_f32 v18, v82, v18, v86
	v_mul_f32_e32 v22, v22, v82
	v_fma_f32 v19, v83, v19, v87
	v_mul_f32_e32 v23, v23, v83
	global_store_dwordx4 v0, v[16:19], s[24:25] offset:0
	global_store_dwordx4 v0, v[20:23], s[26:27] offset:0
	s_waitcnt vmcnt(14)
	v_fma_f32 v16, v88, v16, v92
	v_mul_f32_e32 v20, v20, v88
	v_fma_f32 v17, v89, v17, v93
	v_mul_f32_e32 v21, v21, v89
	v_fma_f32 v18, v90, v18, v94
	v_mul_f32_e32 v22, v22, v90
	v_fma_f32 v19, v91, v19, v95
	v_mul_f32_e32 v23, v23, v91
	global_store_dwordx4 v0, v[16:19], s[24:25] offset:2048
	global_store_dwordx4 v0, v[20:23], s[26:27] offset:2048
	s_add_u32 s24, s24, 0x1000
	s_addc_u32 s25, s25, 0
	s_add_u32 s26, s26, 0x1000
	s_addc_u32 s27, s27, 0
	s_lshl_b32 s0, s44, 11
	s_add_u32 s6, s18, s0
	s_addc_u32 s7, s19, 0
	s_add_u32 s6, s6, 0x26200000
	s_addc_u32 s7, s7, 0
	s_add_u32 s8, s6, 0x40000
	s_addc_u32 s9, s7, 0
	s_nop 0
	global_store_dwordx4 v0, v[20:23], s[6:7]
	global_store_dwordx4 v0, v[16:19], s[8:9]
	v_readlane_b32 s45, v254, 38
	s_nop 0
	s_add_i32 s44, s44, s45
	s_cmpk_gt_i32 s44, 0x7f
	s_cbranch_scc0 .Lrgs_seg
.Lrgs_done:
	s_or_b64 exec, exec, s[4:5]
	v_readlane_b32 s45, v254, 38
